# speedup vs baseline: 1.0521x; 1.0521x over previous
; __global__ void __launch_bounds__(NTHR) fwd_megakernel(Params p) {
;   __shared__ __attribute__((aligned(1024))) char shm[131072 + 2048];
;   cg::grid_group grid = cg::this_grid();
;   char* ws = p.ws;
;   float* ss = (float*)(ws + OFF_SUMSQ);
;   const u16* abf = (const u16*)(ws + OFF_ABF);
;   phase0(p, shm);
_Z14fwd_megakernel6Params:
	s_load_dwordx16 s[40:55], s[0:1], 0x0
	s_load_dwordx16 s[56:71], s[0:1], 0x40
	s_load_dwordx4 s[72:75], s[0:1], 0x80
	s_load_dword s3, s[0:1], 0x90
	s_add_u32 s76, s0, 0x90
	s_addc_u32 s77, s1, 0
	s_cmp_lg_u32 s2, 0
	s_cbranch_scc1 .Lxb_init_done
	v_cmp_eq_u32_e32 vcc, 0, v0
	s_and_saveexec_b64 s[98:99], vcc
	s_cbranch_execz .Lxb_init_end
	s_waitcnt lgkmcnt(0)
	s_add_u32 s100, s74, 0x7620900
	s_addc_u32 s101, s75, 0
	v_mov_b32_e32 v1, 0
	v_mov_b32_e32 v2, 0x100
	global_atomic_swap v2, v1, s[100:101]
	v_mov_b32_e32 v2, 0x1000
	s_mov_b32 vcc_lo, 32
.Lxb_init_loop:
	global_atomic_swap v2, v1, s[100:101]
	v_add_u32_e32 v2, 0x100, v2
	s_sub_u32 vcc_lo, vcc_lo, 1
	s_cmp_lg_u32 vcc_lo, 0
	s_cbranch_scc1 .Lxb_init_loop
	s_waitcnt vmcnt(0)
	v_mov_b32_e32 v2, 0
	v_mov_b32_e32 v1, 0x51a7b3d9
	global_atomic_swap v2, v1, s[100:101]
.Lxb_init_end:
	s_or_b64 exec, exec, s[98:99]
.Lxb_init_done:
	v_and_b32_e32 v220, 0x3ff, v0
	s_cmpk_lt_i32 s2, 0x1a80
	v_mov_b32_e32 v10, v220
	s_cselect_b64 s[6:7], -1, 0
	s_cmpk_gt_i32 s2, 0x1a7f
	s_cbranch_scc1 .LBB0_9
	s_movk_i32 s33, 0x400
	s_cmpk_lt_i32 s2, 0x400
	s_mov_b64 s[10:11], -1
	s_cbranch_scc1 .LBB0_10
	s_cmpk_gt_u32 s2, 0x4ff
	s_cbranch_scc0 .LBB0_11
	s_cmpk_gt_u32 s2, 0xa7f
	s_cbranch_scc0 .LBB0_12
	s_cmpk_gt_u32 s2, 0xfff
	s_cbranch_scc0 .LBB0_13
	s_cmpk_gt_u32 s2, 0x12bf
	s_cbranch_scc0 .LBB0_14
	s_cmpk_gt_u32 s2, 0x157f
	s_cbranch_scc0 .LBB0_15
	s_cmpk_gt_u32 s2, 0x197f
	s_mov_b64 s[14:15], -1
	s_cbranch_scc0 .LBB0_16
	s_add_i32 s20, s2, 0xffffe680
	s_waitcnt lgkmcnt(0)
	s_add_u32 s4, s74, 0x3300000
	s_addc_u32 s5, s75, 0
	s_mov_b64 s[8:9], 0
	s_mov_b64 s[0:1], s[66:67]
	s_branch .LBB0_17

; DEVI void phase_cumsum(const Params& p, char* shm) {
;   float* lf = (float*)(p.ws + OFF_LF);
;   float* sc = (float*)shm;
;   const int tid = threadIdx.x;
;   for (int chain = blockIdx.x; chain < NB * 16; chain += gridDim.x) {
;     float* a = lf + (size_t)chain * LP;
;     constexpr int PER = 17;
;     float v[PER]; float run = 0.f;
; #pragma unroll
;     for (int i = 0; i < PER; ++i) { int idx = tid * PER + i; float x = idx < LP ? a[idx] : 0.f; run += x; v[i] = run; }
;     sc[tid] = run; __syncthreads();
; __global__ void __launch_bounds__(NTHR) fwd_megakernel(Params p) {
;     ...
;   grid.sync();
;   phase_cumsum(p, shm);
.LBB0_140:
	s_or_b64 exec, exec, s[50:51]
	v_lshrrev_b32_e32 v1, 20, v0
	v_lshrrev_b32_e32 v0, 10, v0
	v_or_b32_e32 v0, v0, v1
	s_movk_i32 s0, 0x3ff
	v_and_or_b32 v0, v0, s0, v220
	v_cmp_eq_u32_e64 s[0:1], 0, v0
	s_waitcnt lgkmcnt(0)
	s_waitcnt vmcnt(0)
	s_barrier
	s_and_saveexec_b64 s[4:5], s[0:1]
	s_cbranch_execz .LBB0_150
	buffer_wbl2 sc1
	s_waitcnt vmcnt(0)
	s_load_dword s8, s[76:77], 0x0
	s_add_u32 s6, s74, 0x7620900
	s_addc_u32 s7, s75, 0
	v_mov_b32_e32 v2, 0
	s_mov_b32 s10, 0xfffff
.Lxb_flag:
	global_load_dword v0, v2, s[6:7] sc1
	s_waitcnt vmcnt(0)
	v_readfirstlane_b32 s9, v0
	s_nop 0
	s_cmp_eq_u32 s9, 0x51a7b3d9
	s_cbranch_scc1 .Lxb_flag_ok
	s_sub_u32 s10, s10, 1
	s_cbranch_scc1 .Lxb_flag_ok
	s_sleep 1
	s_branch .Lxb_flag
.Lxb_flag_ok:
	v_mov_b32_e32 v2, 0x100
	v_mov_b32_e32 v3, 1
	global_atomic_add v3, v2, v3, s[6:7] sc0
	s_waitcnt lgkmcnt(0)
	s_mul_i32 s8, s8, 1
	s_waitcnt vmcnt(0)
	v_readfirstlane_b32 s9, v3
	s_nop 0
	s_add_u32 s9, s9, 1
	s_cmp_lg_u32 s9, s8
	s_cbranch_scc1 .Lxb_wait_1
	v_mov_b32_e32 v2, 0x1000
	v_mov_b32_e32 v3, 1
	s_mov_b32 s10, 32
.Lxb_rel_1:
	global_atomic_umax v2, v3, s[6:7]
	v_add_u32_e32 v2, 0x100, v2
	s_sub_u32 s10, s10, 1
	s_cmp_lg_u32 s10, 0
	s_cbranch_scc1 .Lxb_rel_1
	s_branch .Lxb_done_1
.Lxb_wait_1:
	s_and_b32 s9, s2, 31
	s_lshl_b32 s9, s9, 8
	s_add_u32 s9, s9, 0x1000
	v_mov_b32_e32 v2, s9
	s_mov_b32 s10, 0xffff
.Lxb_poll_1:
	global_load_dword v0, v2, s[6:7] sc1
	s_waitcnt vmcnt(0)
	v_readfirstlane_b32 s9, v0
	s_nop 0
	s_cmp_ge_u32 s9, 1
	s_cbranch_scc1 .Lxb_done_1
	s_sub_u32 s10, s10, 1
	s_cbranch_scc1 .Lxb_done_1
	s_sleep 1
	s_branch .Lxb_poll_1
.Lxb_done_1:
	buffer_inv sc1
	s_waitcnt vmcnt(0)
.LBB0_150:
	s_or_b64 exec, exec, s[4:5]
	s_cmp_lt_i32 s2, 64
	s_cselect_b64 s[24:25], -1, 0
	s_cmp_gt_i32 s2, 63
	s_barrier
	s_cbranch_scc1 .LBB0_209
	s_movk_i32 s4, 0x1e6
	s_waitcnt vmcnt(4)
	v_lshlrev_b32_e32 v17, 2, v220
	v_mul_u32_u24_e32 v0, 17, v220
	v_cmp_gt_u32_e32 vcc, s4, v220
	s_movk_i32 s4, 0x1e5
	s_movk_i32 s18, 0x7f
	s_movk_i32 s20, 0xff
	v_cmp_gt_u32_e64 s[22:23], s4, v220
	v_cmp_ne_u32_e64 s[4:5], 0, v220
	v_add_u32_e32 v18, -4, v17
	v_cmp_lt_u32_e64 s[6:7], 1, v220
	v_cmp_lt_u32_e64 s[8:9], 3, v220
	v_add_u32_e32 v19, -16, v17
	v_cmp_lt_u32_e64 s[10:11], 7, v220
	v_cmp_lt_u32_e64 s[12:13], 15, v220
	v_subrev_u32_e32 v20, 64, v17
	v_cmp_lt_u32_e64 s[14:15], 31, v220
	v_cmp_lt_u32_e64 s[16:17], 63, v220
	v_add_u32_e32 v21, 0xffffff00, v17
	v_cmp_lt_u32_e64 s[18:19], s18, v220
	v_cmp_lt_u32_e64 s[20:21], s20, v220
	v_add_u32_e32 v22, 0xfffffc00, v17
	s_mov_b32 s26, 0x3fb8aa3b
	v_lshlrev_b32_e32 v23, 2, v0
	s_mov_b32 s27, s2
	s_branch .LBB0_153

; __global__ void __launch_bounds__(NTHR) fwd_megakernel(Params p) {
;     ...
;   grid.sync();
.LBB0_255:
	s_waitcnt vmcnt(0)
	s_barrier
	s_and_saveexec_b64 s[4:5], s[0:1]
	s_cbranch_execz .LBB0_265
	buffer_wbl2 sc1
	s_waitcnt vmcnt(0)
	s_load_dword s8, s[76:77], 0x0
	s_add_u32 s6, s74, 0x7620900
	s_addc_u32 s7, s75, 0
	s_cmp_lg_u32 s2, 0
	s_cbranch_scc1 .Lxb_noreset
	v_mov_b32_e32 v2, 0
	v_mov_b32_e32 v3, 0
	global_atomic_swap v2, v3, s[6:7]
.Lxb_noreset:
	v_mov_b32_e32 v2, 0x100
	v_mov_b32_e32 v3, 1
	global_atomic_add v3, v2, v3, s[6:7] sc0
	s_waitcnt lgkmcnt(0)
	s_mul_i32 s8, s8, 2
	s_waitcnt vmcnt(0)
	v_readfirstlane_b32 s9, v3
	s_nop 0
	s_add_u32 s9, s9, 1
	s_cmp_lg_u32 s9, s8
	s_cbranch_scc1 .Lxb_wait_2
	v_mov_b32_e32 v2, 0x1000
	v_mov_b32_e32 v3, 2
	s_mov_b32 s10, 32

; __global__ void __launch_bounds__(NTHR) fwd_megakernel(Params p) {
;     ...
;   grid.sync();
.Lxb_poll_2:
	global_load_dword v0, v2, s[6:7] sc1
	s_waitcnt vmcnt(0)
	v_readfirstlane_b32 s9, v0
	s_nop 0
	s_cmp_ge_u32 s9, 2
	s_cbranch_scc1 .Lxb_done_2
	s_sub_u32 s10, s10, 1
	s_cbranch_scc1 .Lxb_done_2
	s_sleep 1
	s_branch .Lxb_poll_2

; __global__ void __launch_bounds__(NTHR) fwd_megakernel(Params p) {
;     ...
;   grid.sync();
.LBB0_356:
	s_waitcnt vmcnt(0)
	s_barrier
	s_and_saveexec_b64 s[4:5], s[0:1]
	s_cbranch_execz .LBB0_366
	buffer_wbl2 sc1
	s_waitcnt vmcnt(0)
	s_load_dword s8, s[76:77], 0x0
	s_add_u32 s6, s74, 0x7620900
	s_addc_u32 s7, s75, 0
	v_mov_b32_e32 v2, 0x100
	v_mov_b32_e32 v3, 1
	global_atomic_add v3, v2, v3, s[6:7] sc0
	s_waitcnt lgkmcnt(0)
	s_mul_i32 s8, s8, 3
	s_waitcnt vmcnt(0)
	v_readfirstlane_b32 s9, v3
	s_nop 0
	s_add_u32 s9, s9, 1
	s_cmp_lg_u32 s9, s8
	s_cbranch_scc1 .Lxb_wait_3
	v_mov_b32_e32 v2, 0x1000
	v_mov_b32_e32 v3, 3
	s_mov_b32 s10, 32

; __global__ void __launch_bounds__(NTHR) fwd_megakernel(Params p) {
;     ...
;   grid.sync();
.Lxb_poll_3:
	global_load_dword v0, v2, s[6:7] sc1
	s_waitcnt vmcnt(0)
	v_readfirstlane_b32 s9, v0
	s_nop 0
	s_cmp_ge_u32 s9, 3
	s_cbranch_scc1 .Lxb_done_3
	s_sub_u32 s10, s10, 1
	s_cbranch_scc1 .Lxb_done_3
	s_sleep 1
	s_branch .Lxb_poll_3

; __global__ void __launch_bounds__(NTHR) fwd_megakernel(Params p) {
;     ...
;   grid.sync();
.LBB0_402:
	s_waitcnt vmcnt(0)
	s_barrier
	s_and_saveexec_b64 s[4:5], s[0:1]
	s_cbranch_execz .LBB0_412
	buffer_wbl2 sc1
	s_waitcnt vmcnt(0)
	s_load_dword s16, s[76:77], 0x0
	s_add_u32 s12, s74, 0x7620900
	s_addc_u32 s13, s75, 0
	v_mov_b32_e32 v2, 0x100
	v_mov_b32_e32 v3, 1
	global_atomic_add v3, v2, v3, s[12:13] sc0
	s_waitcnt lgkmcnt(0)
	s_mul_i32 s16, s16, 4
	s_waitcnt vmcnt(0)
	v_readfirstlane_b32 s17, v3
	s_nop 0
	s_add_u32 s17, s17, 1
	s_cmp_lg_u32 s17, s16
	s_cbranch_scc1 .Lxb_wait_4
	v_mov_b32_e32 v2, 0x1000
	v_mov_b32_e32 v3, 4
	s_mov_b32 s18, 32
.Lxb_rel_4:
	global_atomic_umax v2, v3, s[12:13]
	v_add_u32_e32 v2, 0x100, v2
	s_sub_u32 s18, s18, 1
	s_cmp_lg_u32 s18, 0
	s_cbranch_scc1 .Lxb_rel_4
	s_branch .Lxb_done_4
.Lxb_wait_4:
	s_and_b32 s17, s2, 31
	s_lshl_b32 s17, s17, 8
	s_add_u32 s17, s17, 0x1000
	v_mov_b32_e32 v2, s17
	s_mov_b32 s18, 0xffff
.Lxb_poll_4:
	global_load_dword v0, v2, s[12:13] sc1
	s_waitcnt vmcnt(0)
	v_readfirstlane_b32 s17, v0
	s_nop 0
	s_cmp_ge_u32 s17, 4
	s_cbranch_scc1 .Lxb_done_4
	s_sub_u32 s18, s18, 1
	s_cbranch_scc1 .Lxb_done_4
	s_sleep 1
	s_branch .Lxb_poll_4

; __global__ void __launch_bounds__(NTHR) fwd_megakernel(Params p) {
;     ...
;   grid.sync();
.LBB0_428:
	s_waitcnt vmcnt(0)
	s_barrier
	s_and_saveexec_b64 s[4:5], s[0:1]
	s_cbranch_execz .LBB0_438
	buffer_wbl2 sc1
	s_waitcnt vmcnt(0)
	s_load_dword s12, s[76:77], 0x0
	s_add_u32 s10, s74, 0x7620900
	s_addc_u32 s11, s75, 0
	v_mov_b32_e32 v2, 0x100
	v_mov_b32_e32 v3, 1
	global_atomic_add v3, v2, v3, s[10:11] sc0
	s_waitcnt lgkmcnt(0)
	s_mul_i32 s12, s12, 5
	s_waitcnt vmcnt(0)
	v_readfirstlane_b32 s13, v3
	s_nop 0
	s_add_u32 s13, s13, 1
	s_cmp_lg_u32 s13, s12
	s_cbranch_scc1 .Lxb_wait_5
	v_mov_b32_e32 v2, 0x1000
	v_mov_b32_e32 v3, 5
	s_mov_b32 s16, 32
.Lxb_rel_5:
	global_atomic_umax v2, v3, s[10:11]
	v_add_u32_e32 v2, 0x100, v2
	s_sub_u32 s16, s16, 1
	s_cmp_lg_u32 s16, 0
	s_cbranch_scc1 .Lxb_rel_5
	s_branch .Lxb_done_5
.Lxb_wait_5:
	s_and_b32 s13, s2, 31
	s_lshl_b32 s13, s13, 8
	s_add_u32 s13, s13, 0x1000
	v_mov_b32_e32 v2, s13
	s_mov_b32 s16, 0xffff
.Lxb_poll_5:
	global_load_dword v0, v2, s[10:11] sc1
	s_waitcnt vmcnt(0)
	v_readfirstlane_b32 s13, v0
	s_nop 0
	s_cmp_ge_u32 s13, 5
	s_cbranch_scc1 .Lxb_done_5
	s_sub_u32 s16, s16, 1
	s_cbranch_scc1 .Lxb_done_5
	s_sleep 1
	s_branch .Lxb_poll_5

; __global__ void __launch_bounds__(NTHR) fwd_megakernel(Params p) {
;     ...
;   grid.sync();
.LBB0_474:
	s_waitcnt vmcnt(0)
	s_barrier
	s_and_saveexec_b64 s[8:9], s[0:1]
	s_cbranch_execz .LBB0_484
	buffer_wbl2 sc1
	s_waitcnt vmcnt(0)
	s_load_dword s12, s[76:77], 0x0
	s_add_u32 s10, s74, 0x7620900
	s_addc_u32 s11, s75, 0
	v_mov_b32_e32 v2, 0x100
	v_mov_b32_e32 v3, 1
	global_atomic_add v3, v2, v3, s[10:11] sc0
	s_waitcnt lgkmcnt(0)
	s_mul_i32 s12, s12, 6
	s_waitcnt vmcnt(0)
	v_readfirstlane_b32 s13, v3
	s_nop 0
	s_add_u32 s13, s13, 1
	s_cmp_lg_u32 s13, s12
	s_cbranch_scc1 .Lxb_wait_6
	v_mov_b32_e32 v2, 0x1000
	v_mov_b32_e32 v3, 6
	s_mov_b32 s16, 32

; __global__ void __launch_bounds__(NTHR) fwd_megakernel(Params p) {
;     ...
;   grid.sync();
.Lxb_poll_6:
	global_load_dword v0, v2, s[10:11] sc1
	s_waitcnt vmcnt(0)
	v_readfirstlane_b32 s13, v0
	s_nop 0
	s_cmp_ge_u32 s13, 6
	s_cbranch_scc1 .Lxb_done_6
	s_sub_u32 s16, s16, 1
	s_cbranch_scc1 .Lxb_done_6
	s_sleep 1
	s_branch .Lxb_poll_6

; __global__ void __launch_bounds__(NTHR) fwd_megakernel(Params p) {
;     ...
;   grid.sync();
.LBB0_509:
	s_waitcnt vmcnt(0)
	s_barrier
	s_and_saveexec_b64 s[8:9], s[0:1]
	s_cbranch_execz .LBB0_519
	buffer_wbl2 sc1
	s_waitcnt vmcnt(0)
	s_load_dword s12, s[76:77], 0x0
	s_add_u32 s10, s74, 0x7620900
	s_addc_u32 s11, s75, 0
	v_mov_b32_e32 v2, 0x100
	v_mov_b32_e32 v3, 1
	global_atomic_add v3, v2, v3, s[10:11] sc0
	s_waitcnt lgkmcnt(0)
	s_mul_i32 s12, s12, 7
	s_waitcnt vmcnt(0)
	v_readfirstlane_b32 s13, v3
	s_nop 0
	s_add_u32 s13, s13, 1
	s_cmp_lg_u32 s13, s12
	s_cbranch_scc1 .Lxb_wait_7
	v_mov_b32_e32 v2, 0x1000
	v_mov_b32_e32 v3, 7
	s_mov_b32 s14, 32
.Lxb_rel_7:
	global_atomic_umax v2, v3, s[10:11]
	v_add_u32_e32 v2, 0x100, v2
	s_sub_u32 s14, s14, 1
	s_cmp_lg_u32 s14, 0
	s_cbranch_scc1 .Lxb_rel_7
	s_branch .Lxb_done_7
.Lxb_wait_7:
	s_and_b32 s13, s2, 31
	s_lshl_b32 s13, s13, 8
	s_add_u32 s13, s13, 0x1000
	v_mov_b32_e32 v2, s13
	s_mov_b32 s14, 0xffff
.Lxb_poll_7:
	global_load_dword v0, v2, s[10:11] sc1
	s_waitcnt vmcnt(0)
	v_readfirstlane_b32 s13, v0
	s_nop 0
	s_cmp_ge_u32 s13, 7
	s_cbranch_scc1 .Lxb_done_7
	s_sub_u32 s14, s14, 1
	s_cbranch_scc1 .Lxb_done_7
	s_sleep 1
	s_branch .Lxb_poll_7

; __global__ void __launch_bounds__(NTHR) fwd_megakernel(Params p) {
;     ...
;   grid.sync();
.LBB0_560:
	s_waitcnt vmcnt(0)
	s_barrier
	s_and_saveexec_b64 s[8:9], s[0:1]
	s_cbranch_execz .LBB0_570
	buffer_wbl2 sc1
	s_waitcnt vmcnt(0)
	s_load_dword s12, s[76:77], 0x0
	s_add_u32 s10, s74, 0x7620900
	s_addc_u32 s11, s75, 0
	v_mov_b32_e32 v2, 0x100
	v_mov_b32_e32 v3, 1
	global_atomic_add v3, v2, v3, s[10:11] sc0
	s_waitcnt lgkmcnt(0)
	s_mul_i32 s12, s12, 8
	s_waitcnt vmcnt(0)
	v_readfirstlane_b32 s13, v3
	s_nop 0
	s_add_u32 s13, s13, 1
	s_cmp_lg_u32 s13, s12
	s_cbranch_scc1 .Lxb_wait_8
	v_mov_b32_e32 v2, 0x1000
	v_mov_b32_e32 v3, 8
	s_mov_b32 s14, 32

; __global__ void __launch_bounds__(NTHR) fwd_megakernel(Params p) {
;     ...
;   grid.sync();
.Lxb_poll_8:
	global_load_dword v0, v2, s[10:11] sc1
	s_waitcnt vmcnt(0)
	v_readfirstlane_b32 s13, v0
	s_nop 0
	s_cmp_ge_u32 s13, 8
	s_cbranch_scc1 .Lxb_done_8
	s_sub_u32 s14, s14, 1
	s_cbranch_scc1 .Lxb_done_8
	s_sleep 1
	s_branch .Lxb_poll_8

; __global__ void __launch_bounds__(NTHR) fwd_megakernel(Params p) {
;     ...
;   grid.sync();
.LBB0_606:
	s_waitcnt vmcnt(0)
	s_barrier
	s_and_saveexec_b64 s[8:9], s[0:1]
	s_cbranch_execz .LBB0_616
	buffer_wbl2 sc1
	s_waitcnt vmcnt(0)
	s_load_dword s14, s[76:77], 0x0
	s_add_u32 s12, s74, 0x7620900
	s_addc_u32 s13, s75, 0
	v_mov_b32_e32 v2, 0x100
	v_mov_b32_e32 v3, 1
	global_atomic_add v3, v2, v3, s[12:13] sc0
	s_waitcnt lgkmcnt(0)
	s_mul_i32 s14, s14, 9
	s_waitcnt vmcnt(0)
	v_readfirstlane_b32 s15, v3
	s_nop 0
	s_add_u32 s15, s15, 1
	s_cmp_lg_u32 s15, s14
	s_cbranch_scc1 .Lxb_wait_9
	v_mov_b32_e32 v2, 0x1000
	v_mov_b32_e32 v3, 9
	s_mov_b32 s16, 32
.Lxb_rel_9:
	global_atomic_umax v2, v3, s[12:13]
	v_add_u32_e32 v2, 0x100, v2
	s_sub_u32 s16, s16, 1
	s_cmp_lg_u32 s16, 0
	s_cbranch_scc1 .Lxb_rel_9
	s_branch .Lxb_done_9
.Lxb_wait_9:
	s_and_b32 s15, s2, 31
	s_lshl_b32 s15, s15, 8
	s_add_u32 s15, s15, 0x1000
	v_mov_b32_e32 v2, s15
	s_mov_b32 s16, 0xffff
.Lxb_poll_9:
	global_load_dword v0, v2, s[12:13] sc1
	s_waitcnt vmcnt(0)
	v_readfirstlane_b32 s15, v0
	s_nop 0
	s_cmp_ge_u32 s15, 9
	s_cbranch_scc1 .Lxb_done_9
	s_sub_u32 s16, s16, 1
	s_cbranch_scc1 .Lxb_done_9
	s_sleep 1
	s_branch .Lxb_poll_9

; __global__ void __launch_bounds__(NTHR) fwd_megakernel(Params p) {
;     ...
;   grid.sync();
.LBB0_632:
	s_waitcnt vmcnt(0)
	s_barrier
	s_and_saveexec_b64 s[8:9], s[0:1]
	s_cbranch_execz .LBB0_642
	buffer_wbl2 sc1
	s_waitcnt vmcnt(0)
	s_load_dword s12, s[76:77], 0x0
	s_add_u32 s10, s74, 0x7620900
	s_addc_u32 s11, s75, 0
	v_mov_b32_e32 v2, 0x100
	v_mov_b32_e32 v3, 1
	global_atomic_add v3, v2, v3, s[10:11] sc0
	s_waitcnt lgkmcnt(0)
	s_mul_i32 s12, s12, 10
	s_waitcnt vmcnt(0)
	v_readfirstlane_b32 s13, v3
	s_nop 0
	s_add_u32 s13, s13, 1
	s_cmp_lg_u32 s13, s12
	s_cbranch_scc1 .Lxb_wait_10
	v_mov_b32_e32 v2, 0x1000
	v_mov_b32_e32 v3, 10
	s_mov_b32 s14, 32

; __global__ void __launch_bounds__(NTHR) fwd_megakernel(Params p) {
;     ...
;   grid.sync();
.Lxb_poll_10:
	global_load_dword v0, v2, s[10:11] sc1
	s_waitcnt vmcnt(0)
	v_readfirstlane_b32 s13, v0
	s_nop 0
	s_cmp_ge_u32 s13, 10
	s_cbranch_scc1 .Lxb_done_10
	s_sub_u32 s14, s14, 1
	s_cbranch_scc1 .Lxb_done_10
	s_sleep 1
	s_branch .Lxb_poll_10

; __global__ void __launch_bounds__(NTHR) fwd_megakernel(Params p) {
;     ...
;   grid.sync();
.LBB0_678:
	s_waitcnt vmcnt(0)
	s_barrier
	s_and_saveexec_b64 s[98:99], s[0:1]
	s_cbranch_execz .LBB0_688
	buffer_wbl2 sc1
	s_waitcnt vmcnt(0)
	s_load_dword s4, s[76:77], 0x0
	s_add_u32 s0, s74, 0x7620900
	s_addc_u32 s1, s75, 0
	v_mov_b32_e32 v2, 0x100
	v_mov_b32_e32 v3, 1
	global_atomic_add v3, v2, v3, s[0:1] sc0
	s_waitcnt lgkmcnt(0)
	s_mul_i32 s4, s4, 11
	s_waitcnt vmcnt(0)
	v_readfirstlane_b32 s5, v3
	s_nop 0
	s_add_u32 s5, s5, 1
	s_cmp_lg_u32 s5, s4
	s_cbranch_scc1 .Lxb_wait_11
	v_mov_b32_e32 v2, 0x1000
	v_mov_b32_e32 v3, 11
	s_mov_b32 s6, 32
.Lxb_rel_11:
	global_atomic_umax v2, v3, s[0:1]
	v_add_u32_e32 v2, 0x100, v2
	s_sub_u32 s6, s6, 1
	s_cmp_lg_u32 s6, 0
	s_cbranch_scc1 .Lxb_rel_11
	s_branch .Lxb_done_11
.Lxb_wait_11:
	s_and_b32 s5, s2, 31
	s_lshl_b32 s5, s5, 8
	s_add_u32 s5, s5, 0x1000
	v_mov_b32_e32 v2, s5
	s_mov_b32 s6, 0xffff
.Lxb_poll_11:
	global_load_dword v0, v2, s[0:1] sc1
	s_waitcnt vmcnt(0)
	v_readfirstlane_b32 s5, v0
	s_nop 0
	s_cmp_ge_u32 s5, 11
	s_cbranch_scc1 .Lxb_done_11
	s_sub_u32 s6, s6, 1
	s_cbranch_scc1 .Lxb_done_11
	s_sleep 1
	s_branch .Lxb_poll_11

; DEVI void phase_final(const Params& p) {
;   const float* ss = (const float*)(p.ws + OFF_SUMSQ) + 4 * MPAD;
;   const u16* abf = (const u16*)(p.ws + OFF_ABF);
;   int tid = threadIdx.x;
;   asm volatile("" : "+v"(tid));
;   const int wid = tid >> 6, lane = tid & 63;
;   f32x4 g[4];
; #pragma unroll
;   for (int i = 0; i < 4; ++i) g[i] = *reinterpret_cast<const f32x4*>(p.final_norm + lane * 4 + 256 * i);
;   const int rstep = gridDim.x * 8;
;   int row = blockIdx.x * 8 + wid;
;   u32x2 hv[4]; float sv = 0.f;
;   if (row < MREAL) {
; #pragma unroll
;     for (int i = 0; i < 4; ++i) hv[i] = *reinterpret_cast<const u32x2*>(abf + (size_t)row * DM + lane * 4 + 256 * i);
;     sv = ss[row];
;   }
; __global__ void __launch_bounds__(NTHR) fwd_megakernel(Params p) {
;     ...
;   grid.sync();
;   phase_final(p);
.LBB0_688:
	s_or_b64 exec, exec, s[98:99]
	s_barrier
	s_mov_b32 s12, 0x8000
	v_ashrrev_i32_e32 v0, 6, v220
	v_add_u32_e32 v16, s33, v0
	v_cmp_gt_i32_e32 vcc, s12, v16
	s_and_saveexec_b64 s[0:1], vcc
	s_cbranch_execz .LBB0_693
	v_lshlrev_b32_e32 v0, 2, v220
	v_and_b32_e32 v20, 0xfc, v0
	v_lshlrev_b32_e32 v17, 2, v20
	global_load_dwordx4 v[0:3], v17, s[48:49]
	global_load_dwordx4 v[4:7], v17, s[48:49] offset:1024
	global_load_dwordx4 v[8:11], v17, s[48:49] offset:2048
	global_load_dwordx4 v[12:15], v17, s[48:49] offset:3072
	v_ashrrev_i32_e32 v17, 31, v16
	v_lshlrev_b64 v[18:19], 11, v[16:17]
	v_lshl_add_u64 v[18:19], s[38:39], 0, v[18:19]
	v_lshlrev_b32_e32 v20, 1, v20
	v_mov_b32_e32 v21, 0
	v_lshl_add_u64 v[18:19], v[18:19], 0, v[20:21]
	v_lshl_add_u64 v[20:21], v[16:17], 2, s[8:9]
	global_load_dword v41, v[20:21], off
	global_load_dwordx2 v[30:31], v[18:19], off
	global_load_dwordx2 v[28:29], v[18:19], off offset:512
	global_load_dwordx2 v[26:27], v[18:19], off offset:1024
	global_load_dwordx2 v[24:25], v[18:19], off offset:1536
	v_add_u32_e32 v22, s44, v16
	v_lshlrev_b64 v[18:19], 12, v[16:17]
	v_and_b32_e32 v17, 63, v220
	v_ashrrev_i32_e32 v23, 31, v22
	v_mov_b64_e32 v[20:21], 0x7600400
	v_lshl_or_b32 v18, v17, 4, v18
	s_ashr_i32 s45, s44, 31
	v_lshl_add_u64 v[20:21], v[22:23], 2, v[20:21]
	v_lshlrev_b64 v[22:23], 11, v[22:23]
	v_lshl_add_u64 v[18:19], s[72:73], 0, v[18:19]
	s_lshl_b64 s[2:3], s[44:45], 12
	s_lshl_b64 s[4:5], s[44:45], 2
	v_lshl_or_b32 v22, v17, 3, v22
	s_lshl_b64 s[6:7], s[44:45], 11
	s_mov_b64 s[8:9], 0
	s_movk_i32 s13, 0x7fff
	v_mov_b32_e32 v17, 0x358637bd
	s_waitcnt vmcnt(4)
	v_mov_b32_e32 v40, v41
	s_branch .LBB0_691
